# v114 + the XCD leader's buffer_inv sc1 also moved ahead of its top-level generation spin (issued right after its TOP atomic returns)
# speedup vs baseline: 1.0031x; 1.0031x over previous
; __device__ __forceinline__ unsigned xb_ld(unsigned* p)              { return __hip_atomic_load(p, __ATOMIC_RELAXED, __HIP_MEMORY_SCOPE_AGENT); }
; __device__ __forceinline__ unsigned xb_add(unsigned* p, unsigned v) { return __hip_atomic_fetch_add(p, v, __ATOMIC_RELAXED, __HIP_MEMORY_SCOPE_AGENT); }
; #define XB_SPIN(cond, bar) do { unsigned _sp = 0; while (cond) { __builtin_amdgcn_s_sleep(1); \
;     if ((++_sp & 255u) == 0u) { if (xb_ld(&(bar)[XB_TMO])) break; if (_sp > XB_SPIN_CAP) { atomicAdd(&(bar)[XB_TMO], 1u); break; } } } } while (0)
; __device__ __forceinline__ void xcd_barrier(const XcdBarrier& b) {
;     ...
;         if (old + 1u == (gen + 1u) * nloc) {
;             __builtin_amdgcn_fence(__ATOMIC_RELEASE, "agent");
;             asm volatile("s_waitcnt vmcnt(0)" ::: "memory");
;             const unsigned og = xb_add(&bar[XB_TOP], 1u);
;             const unsigned tg = og / nx;
;             if (og + 1u == (tg + 1u) * nx) xb_add(&bar[XB_TOPGEN], 1u);
;             else XB_SPIN(xb_ld(&bar[XB_TOPGEN]) == tg, bar);
.LBB0_603:
	s_or_b64 exec, exec, s[8:9]
	v_cvt_f32_u32_e32 v4, v1
	s_waitcnt vmcnt(0)
	buffer_inv sc1
	v_readfirstlane_b32 s6, v3
	s_add_u32 s8, s4, 0x3500
	s_addc_u32 s9, s5, 0
	v_rcp_iflag_f32_e32 v4, v4
	v_add_u32_e32 v2, s6, v2
	v_add_u32_e32 v5, 1, v2
	s_mov_b64 s[10:11], -1
	v_mul_f32_e32 v3, 0x4f7ffffe, v4
	v_cvt_u32_f32_e32 v3, v3
	v_sub_u32_e32 v4, 0, v1
	v_mul_lo_u32 v4, v4, v3
	v_mul_hi_u32 v4, v3, v4
	v_add_u32_e32 v3, v3, v4
	v_mul_hi_u32 v3, v2, v3
	v_mul_lo_u32 v4, v3, v1
	v_sub_u32_e32 v2, v2, v4
	v_add_u32_e32 v6, 1, v3
	v_cmp_ge_u32_e32 vcc, v2, v1
	v_sub_u32_e32 v4, v2, v1
	s_nop 0
	v_cndmask_b32_e32 v3, v3, v6, vcc
	v_cndmask_b32_e32 v2, v2, v4, vcc
	v_add_u32_e32 v4, 1, v3
	v_cmp_ge_u32_e32 vcc, v2, v1
	s_nop 1
	v_cndmask_b32_e32 v4, v3, v4, vcc
	v_mul_lo_u32 v2, v1, v4
	v_add_u32_e32 v1, v2, v1
	v_cmp_ne_u32_e32 vcc, v5, v1
	v_mov_b64_e32 v[2:3], s[8:9]
	s_and_saveexec_b64 s[6:7], vcc
	s_cbranch_execz .LBB0_615
	v_mov_b32_e32 v1, 0
	global_load_dword v2, v1, s[8:9] sc1
	s_mov_b64 s[14:15], 0
	s_waitcnt vmcnt(0)
	v_cmp_eq_u32_e32 vcc, v2, v4
	s_and_saveexec_b64 s[12:13], vcc
	s_cbranch_execz .LBB0_614
	s_add_u32 s10, s4, 0x200
	s_addc_u32 s11, s5, 0
	s_mov_b32 s25, 1
	s_branch .LBB0_607

; __device__ __forceinline__ unsigned xb_ld(unsigned* p)              { return __hip_atomic_load(p, __ATOMIC_RELAXED, __HIP_MEMORY_SCOPE_AGENT); }
; __device__ __forceinline__ unsigned xb_add(unsigned* p, unsigned v) { return __hip_atomic_fetch_add(p, v, __ATOMIC_RELAXED, __HIP_MEMORY_SCOPE_AGENT); }
; #define XB_SPIN(cond, bar) do { unsigned _sp = 0; while (cond) { __builtin_amdgcn_s_sleep(1); \
;     if ((++_sp & 255u) == 0u) { if (xb_ld(&(bar)[XB_TMO])) break; if (_sp > XB_SPIN_CAP) { atomicAdd(&(bar)[XB_TMO], 1u); break; } } } } while (0)
; __device__ __forceinline__ void xcd_barrier(const XcdBarrier& b) {
;     ...
;         if (old + 1u == (gen + 1u) * nloc) {
;             __builtin_amdgcn_fence(__ATOMIC_RELEASE, "agent");
;             asm volatile("s_waitcnt vmcnt(0)" ::: "memory");
;             const unsigned og = xb_add(&bar[XB_TOP], 1u);
;             const unsigned tg = og / nx;
;             if (og + 1u == (tg + 1u) * nx) xb_add(&bar[XB_TOPGEN], 1u);
;             else XB_SPIN(xb_ld(&bar[XB_TOPGEN]) == tg, bar);
.LBB0_740:
	s_or_b64 exec, exec, s[6:7]
	s_waitcnt vmcnt(0)
	buffer_inv sc1
	v_readfirstlane_b32 s4, v4
	v_cvt_f32_u32_e32 v4, v2
	v_sub_u32_e32 v5, 0, v2
	v_add_u32_e32 v3, s4, v3
	s_add_u32 s4, s2, 0x3500
	v_rcp_iflag_f32_e32 v4, v4
	s_addc_u32 s5, s3, 0
	s_mov_b64 s[8:9], -1
	v_mul_f32_e32 v4, 0x4f7ffffe, v4
	v_cvt_u32_f32_e32 v4, v4
	v_mul_lo_u32 v5, v5, v4
	v_mul_hi_u32 v5, v4, v5
	v_add_u32_e32 v4, v4, v5
	v_mul_hi_u32 v4, v3, v4
	v_mul_lo_u32 v5, v4, v2
	v_sub_u32_e32 v5, v3, v5
	v_cmp_ge_u32_e32 vcc, v5, v2
	v_add_u32_e32 v6, 1, v4
	v_add_u32_e32 v3, 1, v3
	v_cndmask_b32_e32 v4, v4, v6, vcc
	v_sub_u32_e32 v6, v5, v2
	v_cndmask_b32_e32 v5, v5, v6, vcc
	v_cmp_ge_u32_e32 vcc, v5, v2
	v_add_u32_e32 v5, 1, v4
	s_nop 0
	v_cndmask_b32_e32 v4, v4, v5, vcc
	v_mul_lo_u32 v5, v2, v4
	v_add_u32_e32 v2, v5, v2
	v_cmp_ne_u32_e32 vcc, v3, v2
	v_mov_b64_e32 v[2:3], s[4:5]
	s_and_saveexec_b64 s[6:7], vcc
	s_cbranch_execz .LBB0_752
	global_load_dword v2, v35, s[4:5] sc1
	s_mov_b64 s[12:13], 0
	s_waitcnt vmcnt(0)
	v_cmp_eq_u32_e32 vcc, v2, v4
	s_and_saveexec_b64 s[10:11], vcc
	s_cbranch_execz .LBB0_751
	s_add_u32 s8, s2, 0x200
	s_addc_u32 s9, s3, 0
	s_mov_b32 s24, 1
	s_branch .LBB0_744

; __device__ __forceinline__ unsigned xb_ld(unsigned* p)              { return __hip_atomic_load(p, __ATOMIC_RELAXED, __HIP_MEMORY_SCOPE_AGENT); }
; __device__ __forceinline__ unsigned xb_add(unsigned* p, unsigned v) { return __hip_atomic_fetch_add(p, v, __ATOMIC_RELAXED, __HIP_MEMORY_SCOPE_AGENT); }
; #define XB_SPIN(cond, bar) do { unsigned _sp = 0; while (cond) { __builtin_amdgcn_s_sleep(1); \
;     if ((++_sp & 255u) == 0u) { if (xb_ld(&(bar)[XB_TMO])) break; if (_sp > XB_SPIN_CAP) { atomicAdd(&(bar)[XB_TMO], 1u); break; } } } } while (0)
; __device__ __forceinline__ void xcd_barrier(const XcdBarrier& b) {
;     ...
;         if (old + 1u == (gen + 1u) * nloc) {
;             __builtin_amdgcn_fence(__ATOMIC_RELEASE, "agent");
;             asm volatile("s_waitcnt vmcnt(0)" ::: "memory");
;             const unsigned og = xb_add(&bar[XB_TOP], 1u);
;             const unsigned tg = og / nx;
;             if (og + 1u == (tg + 1u) * nx) xb_add(&bar[XB_TOPGEN], 1u);
;             else XB_SPIN(xb_ld(&bar[XB_TOPGEN]) == tg, bar);
.LBB0_1007:
	s_or_b64 exec, exec, s[8:9]
	s_waitcnt vmcnt(0)
	buffer_inv sc1
	v_readfirstlane_b32 s6, v4
	v_cvt_f32_u32_e32 v4, v2
	v_sub_u32_e32 v5, 0, v2
	v_add_u32_e32 v3, s6, v3
	s_add_u32 s6, s4, 0x3500
	v_rcp_iflag_f32_e32 v4, v4
	s_addc_u32 s7, s5, 0
	s_mov_b64 s[10:11], -1
	v_mul_f32_e32 v4, 0x4f7ffffe, v4
	v_cvt_u32_f32_e32 v4, v4
	v_mul_lo_u32 v5, v5, v4
	v_mul_hi_u32 v5, v4, v5
	v_add_u32_e32 v4, v4, v5
	v_mul_hi_u32 v4, v3, v4
	v_mul_lo_u32 v5, v4, v2
	v_sub_u32_e32 v5, v3, v5
	v_cmp_ge_u32_e32 vcc, v5, v2
	v_add_u32_e32 v6, 1, v4
	v_add_u32_e32 v3, 1, v3
	v_cndmask_b32_e32 v4, v4, v6, vcc
	v_sub_u32_e32 v6, v5, v2
	v_cndmask_b32_e32 v5, v5, v6, vcc
	v_cmp_ge_u32_e32 vcc, v5, v2
	v_add_u32_e32 v5, 1, v4
	s_nop 0
	v_cndmask_b32_e32 v4, v4, v5, vcc
	v_mul_lo_u32 v5, v2, v4
	v_add_u32_e32 v2, v5, v2
	v_cmp_ne_u32_e32 vcc, v3, v2
	v_mov_b64_e32 v[2:3], s[6:7]
	s_and_saveexec_b64 s[8:9], vcc
	s_cbranch_execz .LBB0_1019
	global_load_dword v2, v35, s[6:7] sc1
	s_mov_b64 s[14:15], 0
	s_waitcnt vmcnt(0)
	v_cmp_eq_u32_e32 vcc, v2, v4
	s_and_saveexec_b64 s[12:13], vcc
	s_cbranch_execz .LBB0_1018
	s_add_u32 s10, s4, 0x200
	s_addc_u32 s11, s5, 0
	s_mov_b32 s26, 1
	s_branch .LBB0_1011

; __device__ __forceinline__ unsigned xb_ld(unsigned* p)              { return __hip_atomic_load(p, __ATOMIC_RELAXED, __HIP_MEMORY_SCOPE_AGENT); }
; __device__ __forceinline__ unsigned xb_add(unsigned* p, unsigned v) { return __hip_atomic_fetch_add(p, v, __ATOMIC_RELAXED, __HIP_MEMORY_SCOPE_AGENT); }
; #define XB_SPIN(cond, bar) do { unsigned _sp = 0; while (cond) { __builtin_amdgcn_s_sleep(1); \
;     if ((++_sp & 255u) == 0u) { if (xb_ld(&(bar)[XB_TMO])) break; if (_sp > XB_SPIN_CAP) { atomicAdd(&(bar)[XB_TMO], 1u); break; } } } } while (0)
; __device__ __forceinline__ void xcd_barrier(const XcdBarrier& b) {
;     ...
;         if (old + 1u == (gen + 1u) * nloc) {
;             __builtin_amdgcn_fence(__ATOMIC_RELEASE, "agent");
;             asm volatile("s_waitcnt vmcnt(0)" ::: "memory");
;             const unsigned og = xb_add(&bar[XB_TOP], 1u);
;             const unsigned tg = og / nx;
;             if (og + 1u == (tg + 1u) * nx) xb_add(&bar[XB_TOPGEN], 1u);
;             else XB_SPIN(xb_ld(&bar[XB_TOPGEN]) == tg, bar);
.LBB0_1585:
	s_or_b64 exec, exec, s[8:9]
	s_waitcnt vmcnt(0)
	buffer_inv sc1
	v_readfirstlane_b32 s6, v4
	v_cvt_f32_u32_e32 v4, v2
	v_sub_u32_e32 v5, 0, v2
	v_add_u32_e32 v3, s6, v3
	s_add_u32 s6, s2, 0x3500
	v_rcp_iflag_f32_e32 v4, v4
	s_addc_u32 s7, s3, 0
	s_mov_b64 s[10:11], -1
	v_mul_f32_e32 v4, 0x4f7ffffe, v4
	v_cvt_u32_f32_e32 v4, v4
	v_mul_lo_u32 v5, v5, v4
	v_mul_hi_u32 v5, v4, v5
	v_add_u32_e32 v4, v4, v5
	v_mul_hi_u32 v4, v3, v4
	v_mul_lo_u32 v5, v4, v2
	v_sub_u32_e32 v5, v3, v5
	v_cmp_ge_u32_e32 vcc, v5, v2
	v_add_u32_e32 v6, 1, v4
	v_add_u32_e32 v3, 1, v3
	v_cndmask_b32_e32 v4, v4, v6, vcc
	v_sub_u32_e32 v6, v5, v2
	v_cndmask_b32_e32 v5, v5, v6, vcc
	v_cmp_ge_u32_e32 vcc, v5, v2
	v_add_u32_e32 v5, 1, v4
	s_nop 0
	v_cndmask_b32_e32 v4, v4, v5, vcc
	v_mul_lo_u32 v5, v2, v4
	v_add_u32_e32 v2, v5, v2
	v_cmp_ne_u32_e32 vcc, v3, v2
	v_mov_b64_e32 v[2:3], s[6:7]
	s_and_saveexec_b64 s[8:9], vcc
	s_cbranch_execz .LBB0_1597
	global_load_dword v2, v35, s[6:7] sc1
	s_mov_b64 s[14:15], 0
	s_waitcnt vmcnt(0)
	v_cmp_eq_u32_e32 vcc, v2, v4
	s_and_saveexec_b64 s[12:13], vcc
	s_cbranch_execz .LBB0_1596
	s_add_u32 s10, s2, 0x200
	s_addc_u32 s11, s3, 0
	s_mov_b32 s25, 1
	s_branch .LBB0_1589

; __device__ __forceinline__ unsigned xb_ld(unsigned* p)              { return __hip_atomic_load(p, __ATOMIC_RELAXED, __HIP_MEMORY_SCOPE_AGENT); }
; __device__ __forceinline__ unsigned xb_add(unsigned* p, unsigned v) { return __hip_atomic_fetch_add(p, v, __ATOMIC_RELAXED, __HIP_MEMORY_SCOPE_AGENT); }
; #define XB_SPIN(cond, bar) do { unsigned _sp = 0; while (cond) { __builtin_amdgcn_s_sleep(1); \
;     if ((++_sp & 255u) == 0u) { if (xb_ld(&(bar)[XB_TMO])) break; if (_sp > XB_SPIN_CAP) { atomicAdd(&(bar)[XB_TMO], 1u); break; } } } } while (0)
; __device__ __forceinline__ void xcd_barrier(const XcdBarrier& b) {
;     ...
;         if (old + 1u == (gen + 1u) * nloc) {
;             __builtin_amdgcn_fence(__ATOMIC_RELEASE, "agent");
;             asm volatile("s_waitcnt vmcnt(0)" ::: "memory");
;             const unsigned og = xb_add(&bar[XB_TOP], 1u);
;             const unsigned tg = og / nx;
;             if (og + 1u == (tg + 1u) * nx) xb_add(&bar[XB_TOPGEN], 1u);
;             else XB_SPIN(xb_ld(&bar[XB_TOPGEN]) == tg, bar);
.LBB0_2112:
	s_or_b64 exec, exec, s[6:7]
	s_waitcnt vmcnt(0)
	buffer_inv sc1
	v_readfirstlane_b32 s4, v4
	v_cvt_f32_u32_e32 v4, v2
	v_sub_u32_e32 v5, 0, v2
	v_add_u32_e32 v3, s4, v3
	s_add_u32 s4, s2, 0x3500
	v_rcp_iflag_f32_e32 v4, v4
	s_addc_u32 s5, s3, 0
	s_mov_b64 s[8:9], -1
	v_mul_f32_e32 v4, 0x4f7ffffe, v4
	v_cvt_u32_f32_e32 v4, v4
	v_mul_lo_u32 v5, v5, v4
	v_mul_hi_u32 v5, v4, v5
	v_add_u32_e32 v4, v4, v5
	v_mul_hi_u32 v4, v3, v4
	v_mul_lo_u32 v5, v4, v2
	v_sub_u32_e32 v5, v3, v5
	v_cmp_ge_u32_e32 vcc, v5, v2
	v_add_u32_e32 v6, 1, v4
	v_add_u32_e32 v3, 1, v3
	v_cndmask_b32_e32 v4, v4, v6, vcc
	v_sub_u32_e32 v6, v5, v2
	v_cndmask_b32_e32 v5, v5, v6, vcc
	v_cmp_ge_u32_e32 vcc, v5, v2
	v_add_u32_e32 v5, 1, v4
	s_nop 0
	v_cndmask_b32_e32 v4, v4, v5, vcc
	v_mul_lo_u32 v5, v2, v4
	v_add_u32_e32 v2, v5, v2
	v_cmp_ne_u32_e32 vcc, v3, v2
	v_mov_b64_e32 v[2:3], s[4:5]
	s_and_saveexec_b64 s[6:7], vcc
	s_cbranch_execz .LBB0_2124
	global_load_dword v2, v35, s[4:5] sc1
	s_mov_b64 s[12:13], 0
	s_waitcnt vmcnt(0)
	v_cmp_eq_u32_e32 vcc, v2, v4
	s_and_saveexec_b64 s[10:11], vcc
	s_cbranch_execz .LBB0_2123
	s_add_u32 s8, s2, 0x200
	s_addc_u32 s9, s3, 0
	s_mov_b32 s23, 1
	s_branch .LBB0_2116
